# attention steady loop: 32-term scalar row-sum chain -> 15 v_pk_add_f32 + 1 v_add_f32 per tile (same f32 adds, pairwise order)
# baseline (speedup 1.0000x reference)
.LBB0_427:
	s_waitcnt lgkmcnt(1)
	v_mfma_f32_32x32x16_bf16 v[82:97], v[174:177], v[134:137], 0
	v_add_u32_e32 v185, s2, v201
	s_waitcnt lgkmcnt(0)
	v_mfma_f32_32x32x16_bf16 v[66:81], v[170:173], v[134:137], 0
	ds_read_b64_tr_b16 v[170:171], v185 offset:24576
	ds_read_b64_tr_b16 v[172:173], v185 offset:25088
	v_mfma_f32_32x32x16_bf16 v[82:97], v[166:169], v[102:105], v[82:97]
	v_pk_add_f32 v[186:187], v[50:51], v[52:53]
	v_pk_add_f32 v[186:187], v[186:187], v[54:55]
	v_cvt_pk_bf16_f32 v130, v50, v51
	v_cvt_pk_bf16_f32 v131, v52, v53
	ds_read_b64_tr_b16 v[166:167], v185 offset:28672
	ds_read_b64_tr_b16 v[168:169], v185 offset:29184
	v_mfma_f32_32x32x16_bf16 v[66:81], v[162:165], v[102:105], v[66:81]
	v_pk_add_f32 v[186:187], v[186:187], v[56:57]
	v_pk_add_f32 v[186:187], v[186:187], v[58:59]
	v_cvt_pk_bf16_f32 v132, v54, v55
	v_cvt_pk_bf16_f32 v133, v56, v57
	ds_read_b64_tr_b16 v[162:163], v185 offset:25600
	ds_read_b64_tr_b16 v[164:165], v185 offset:26112
	v_mfma_f32_32x32x16_bf16 v[82:97], v[158:161], v[106:109], v[82:97]
	v_pk_add_f32 v[186:187], v[186:187], v[60:61]
	v_pk_add_f32 v[186:187], v[186:187], v[62:63]
	v_cvt_pk_bf16_f32 v126, v58, v59
	v_cvt_pk_bf16_f32 v127, v60, v61
	ds_read_b64_tr_b16 v[58:59], v185 offset:29696
	ds_read_b64_tr_b16 v[60:61], v185 offset:30208
	v_mfma_f32_32x32x16_bf16 v[66:81], v[154:157], v[106:109], v[66:81]
	v_pk_add_f32 v[186:187], v[186:187], v[64:65]
	v_pk_add_f32 v[186:187], v[186:187], v[34:35]
	v_cvt_pk_bf16_f32 v128, v62, v63
	v_cvt_pk_bf16_f32 v129, v64, v65
	ds_read_b64_tr_b16 v[54:55], v185 offset:26624
	ds_read_b64_tr_b16 v[56:57], v185 offset:27136
	v_mfma_f32_32x32x16_bf16 v[82:97], v[150:153], v[110:113], v[82:97]
	v_pk_add_f32 v[186:187], v[186:187], v[36:37]
	v_pk_add_f32 v[186:187], v[186:187], v[38:39]
	v_cvt_pk_bf16_f32 v122, v34, v35
	v_cvt_pk_bf16_f32 v123, v36, v37
	ds_read_b64_tr_b16 v[50:51], v185 offset:30720
	ds_read_b64_tr_b16 v[52:53], v185 offset:31232
	v_mfma_f32_32x32x16_bf16 v[66:81], v[146:149], v[110:113], v[66:81]
	v_pk_add_f32 v[186:187], v[186:187], v[40:41]
	v_pk_add_f32 v[186:187], v[186:187], v[42:43]
	v_cvt_pk_bf16_f32 v124, v38, v39
	v_cvt_pk_bf16_f32 v125, v40, v41
	ds_read_b64_tr_b16 v[38:39], v185 offset:27648
	ds_read_b64_tr_b16 v[40:41], v185 offset:28160
	v_mfma_f32_32x32x16_bf16 v[82:97], v[142:145], v[114:117], v[82:97]
	v_pk_add_f32 v[186:187], v[186:187], v[44:45]
	v_pk_add_f32 v[186:187], v[186:187], v[46:47]
	v_cvt_pk_bf16_f32 v118, v42, v43
	v_cvt_pk_bf16_f32 v119, v44, v45
	ds_read_b64_tr_b16 v[34:35], v185 offset:31744
	ds_read_b64_tr_b16 v[36:37], v185 offset:32256
	v_mfma_f32_32x32x16_bf16 v[66:81], v[138:141], v[114:117], v[66:81]
	v_pk_add_f32 v[186:187], v[186:187], v[48:49]
	v_add_f32_e32 v44, v186, v187
	v_cvt_pk_bf16_f32 v120, v46, v47
	v_cvt_pk_bf16_f32 v121, v48, v49
	v_lshl_add_u64 v[42:43], v[182:183], 0, s[90:91]
	s_add_i32 s0, s8, s74
	s_mov_b32 s2, m0
	s_mov_b32 m0, s0
	s_nop 0
	global_load_lds_dwordx4 v[42:43], off
	s_mov_b32 m0, s2
	v_lshl_add_u64 v[42:43], v[180:181], 0, s[90:91]
	s_add_i32 s0, s6, s79
	s_mov_b32 s2, m0
	s_mov_b32 m0, s0
	s_nop 0
	global_load_lds_dwordx4 v[42:43], off
	s_mov_b32 m0, s2
	v_max_f32_e32 v42, v83, v83
	v_max_f32_e32 v43, v82, v82
	v_max_f32_e32 v42, v43, v42
	v_max3_f32 v43, v84, v85, v67
	v_max3_f32 v42, v42, v66, v68
	v_max3_f32 v42, v42, v69, v86
	v_max3_f32 v43, v43, v88, v89
	v_max3_f32 v42, v42, v87, v70
	v_max3_f32 v43, v43, v72, v73
	v_max3_f32 v42, v42, v71, v90
	v_max3_f32 v43, v43, v92, v93
	v_max3_f32 v42, v42, v91, v74
	v_max3_f32 v43, v43, v76, v77
	v_max3_f32 v42, v42, v75, v94
	v_max3_f32 v43, v43, v96, v97
	v_max3_f32 v42, v42, v95, v78
	v_max3_f32 v43, v43, v80, v81
	v_max3_f32 v42, v42, v79, v43
	v_mov_b32_e32 v43, v42
	s_nop 1
	v_permlane32_swap_b32_e32 v42, v43
	v_max_f32_e32 v43, v43, v43
	v_max_f32_e32 v42, v42, v42
	v_max_f32_e32 v42, v42, v43
	v_cmp_lt_f32_e32 vcc, s75, v42
	s_cmp_lg_u64 vcc, 0
	v_add_f32_e32 v174, v213, v44
	s_cselect_b64 s[2:3], -1, 0
	s_cbranch_vccnz .LBB0_435

.LBB0_430:
	s_add_i32 s0, s6, 0x2000
	s_cmpk_lg_i32 s6, 0x4000
	s_cselect_b32 s85, s0, 0
	s_waitcnt lgkmcnt(1)
	v_mfma_f32_32x32x16_bf16 v[50:65], v[46:49], v[134:137], 0
	v_add_u32_e32 v175, s8, v201
	s_waitcnt lgkmcnt(0)
	v_mfma_f32_32x32x16_bf16 v[34:49], v[42:45], v[134:137], 0
	ds_read_b64_tr_b16 v[150:151], v175 offset:24576
	ds_read_b64_tr_b16 v[152:153], v175 offset:25088
	v_mfma_f32_32x32x16_bf16 v[50:65], v[146:149], v[102:105], v[50:65]
	v_pk_add_f32 v[186:187], v[82:83], v[84:85]
	v_pk_add_f32 v[186:187], v[186:187], v[86:87]
	v_cvt_pk_bf16_f32 v130, v82, v83
	v_cvt_pk_bf16_f32 v131, v84, v85
	ds_read_b64_tr_b16 v[146:147], v175 offset:28672
	ds_read_b64_tr_b16 v[148:149], v175 offset:29184
	v_mfma_f32_32x32x16_bf16 v[34:49], v[138:141], v[102:105], v[34:49]
	v_pk_add_f32 v[186:187], v[186:187], v[88:89]
	v_pk_add_f32 v[186:187], v[186:187], v[90:91]
	v_cvt_pk_bf16_f32 v132, v86, v87
	v_cvt_pk_bf16_f32 v133, v88, v89
	ds_read_b64_tr_b16 v[138:139], v175 offset:25600
	ds_read_b64_tr_b16 v[140:141], v175 offset:26112
	v_mfma_f32_32x32x16_bf16 v[50:65], v[170:173], v[106:109], v[50:65]
	v_pk_add_f32 v[186:187], v[186:187], v[92:93]
	v_pk_add_f32 v[186:187], v[186:187], v[94:95]
	v_cvt_pk_bf16_f32 v126, v90, v91
	v_cvt_pk_bf16_f32 v127, v92, v93
	ds_read_b64_tr_b16 v[90:91], v175 offset:29696
	ds_read_b64_tr_b16 v[92:93], v175 offset:30208
	v_mfma_f32_32x32x16_bf16 v[34:49], v[162:165], v[106:109], v[34:49]
	v_pk_add_f32 v[186:187], v[186:187], v[96:97]
	v_pk_add_f32 v[186:187], v[186:187], v[66:67]
	v_cvt_pk_bf16_f32 v128, v94, v95
	v_cvt_pk_bf16_f32 v129, v96, v97
	ds_read_b64_tr_b16 v[86:87], v175 offset:26624
	ds_read_b64_tr_b16 v[88:89], v175 offset:27136
	v_mfma_f32_32x32x16_bf16 v[50:65], v[166:169], v[110:113], v[50:65]
	v_pk_add_f32 v[186:187], v[186:187], v[68:69]
	v_pk_add_f32 v[186:187], v[186:187], v[70:71]
	v_cvt_pk_bf16_f32 v122, v66, v67
	v_cvt_pk_bf16_f32 v123, v68, v69
	ds_read_b64_tr_b16 v[82:83], v175 offset:30720
	ds_read_b64_tr_b16 v[84:85], v175 offset:31232
	v_mfma_f32_32x32x16_bf16 v[34:49], v[154:157], v[110:113], v[34:49]
	v_pk_add_f32 v[186:187], v[186:187], v[72:73]
	v_pk_add_f32 v[186:187], v[186:187], v[74:75]
	v_cvt_pk_bf16_f32 v124, v70, v71
	v_cvt_pk_bf16_f32 v125, v72, v73
	ds_read_b64_tr_b16 v[70:71], v175 offset:27648
	ds_read_b64_tr_b16 v[72:73], v175 offset:28160
	v_mfma_f32_32x32x16_bf16 v[50:65], v[158:161], v[114:117], v[50:65]
	v_pk_add_f32 v[186:187], v[186:187], v[76:77]
	v_pk_add_f32 v[186:187], v[186:187], v[78:79]
	v_cvt_pk_bf16_f32 v118, v74, v75
	v_cvt_pk_bf16_f32 v119, v76, v77
	ds_read_b64_tr_b16 v[66:67], v175 offset:31744
	ds_read_b64_tr_b16 v[68:69], v175 offset:32256
	v_mfma_f32_32x32x16_bf16 v[34:49], v[142:145], v[114:117], v[34:49]
	v_pk_add_f32 v[186:187], v[186:187], v[80:81]
	v_add_f32_e32 v74, v186, v187
	v_cvt_pk_bf16_f32 v120, v78, v79
	v_cvt_pk_bf16_f32 v121, v80, v81
	v_max_f32_e32 v75, v51, v51
	v_max_f32_e32 v76, v50, v50
	v_max_f32_e32 v75, v76, v75
	s_nop 3
	v_max3_f32 v76, v52, v53, v35
	v_max3_f32 v75, v75, v34, v36
	v_max3_f32 v75, v75, v37, v54
	v_max3_f32 v76, v76, v56, v57
	v_max3_f32 v75, v75, v55, v38
	v_max3_f32 v76, v76, v40, v41
	v_max3_f32 v75, v75, v39, v58
	v_max3_f32 v76, v76, v60, v61
	v_max3_f32 v75, v75, v59, v42
	v_max3_f32 v76, v76, v44, v45
	v_max3_f32 v75, v75, v43, v62
	v_max3_f32 v76, v76, v64, v65
	v_max3_f32 v75, v75, v63, v46
	v_max3_f32 v76, v76, v48, v49
	v_add_f32_e32 v213, v174, v74
	v_max3_f32 v74, v75, v47, v76
	v_mov_b32_e32 v75, v74
	s_nop 1
	v_permlane32_swap_b32_e32 v74, v75
	v_max_f32_e32 v75, v75, v75
	v_max_f32_e32 v74, v74, v74
	s_add_i32 s0, s6, s74
	s_mov_b32 s2, m0
	s_mov_b32 m0, s0
	s_nop 0
	global_load_lds_dwordx4 v[182:183], off
	s_mov_b32 m0, s2
	v_max_f32_e32 v74, v74, v75
	s_add_i32 s0, s85, s79
	s_mov_b32 s2, m0
	s_mov_b32 m0, s0
	s_nop 0
	global_load_lds_dwordx4 v[180:181], off
	s_mov_b32 m0, s2
	v_cmp_lt_f32_e32 vcc, s75, v74
	s_cmp_lg_u64 vcc, 0
	s_cselect_b64 s[2:3], -1, 0
	s_cbranch_vccnz .LBB0_438
